# phase 1: int8 GEMM tile deal balanced against the bf16 GEMM tail (WGs 0..137 take 8 int8 tiles, their ninth go to WGs 138..255), on v36
# speedup vs baseline: 1.0085x; 1.0085x over previous
.LBB0_193:
	s_add_i32 s42, s42, 1
	v_readlane_b32 s20, v254, 0
	s_nop 3
	s_lshl_b32 s4, s42, 8
	s_add_i32 s4, s4, s20
	s_cmpk_lt_u32 s20, 0x8a
	s_cbranch_scc0 .Lp1_light
	s_cmp_lt_u32 s42, 8
	s_cselect_b32 s20, s4, 0x7fffffff
	s_branch .Lp1_done
.Lp1_light:
	s_cmpk_lt_u32 s20, 0xe3
	s_cselect_b32 s5, 9, 8
	s_cselect_b32 vcc_lo, 1, 2
	s_cselect_b32 s21, 0, 1
	s_cmp_lt_u32 s42, s5
	s_cbranch_scc0 .Lp1_extra
	s_mov_b32 s20, s4
	s_branch .Lp1_done
.Lp1_extra:
	s_sub_u32 vcc_hi, s42, s5
	s_sub_u32 s4, s20, 0x8a
	s_sub_u32 s5, s20, 0xe3
	s_lshl_b32 s5, s5, 1
	s_add_u32 s5, s5, 0x59
	s_add_u32 s5, s5, vcc_hi
	s_cmp_eq_u32 s21, 0
	s_cselect_b32 s4, s4, s5
	s_add_u32 s20, s4, 0x800
	s_cmp_lt_u32 vcc_hi, vcc_lo
	s_cselect_b32 s20, s20, 0x7fffffff
	s_cmpk_lt_u32 s4, 0x8a
	s_cselect_b32 s20, s20, 0x7fffffff
.Lp1_done:
	s_mov_b32 s21, 0
	v_cmp_gt_i64_e32 vcc, s[20:21], v[144:145]
	v_cmp_lt_i64_e64 s[4:5], s[20:21], v[142:143]
	s_cbranch_vccnz .LBB0_199
	s_ashr_i32 s16, s20, 31
	s_lshr_b32 s16, s16, 29
	s_add_i32 s18, s20, s16
	s_and_b32 s16, s18, -8
	s_sub_i32 s19, s20, s16
	s_cmp_gt_i32 s19, 2
	s_mov_b64 s[16:17], -1
	s_cbranch_scc0 .LBB0_196
	s_mul_i32 s16, s19, 0x11c
	s_or_b32 s20, s16, 3
	s_mov_b64 s[16:17], 0
